# SSD off-diagonal tile: all five LDS reads issued before the first wait (scalar decay read into v235)
# baseline (speedup 1.0000x reference)
; __device__ __forceinline__ float ex2(float x) { return __builtin_amdgcn_exp2f(x); }
; #define LAS __attribute__((address_space(3)))
; __device__ __forceinline__ void ssd_stream(const Frame& F, const Args& A, int sidx) {
;     ...
;                 if (sti < lt) {
;                     const float fl = ex2(acs_l - arr[32 * sti + 31]);
; #pragma unroll
;                     for (int q4 = 0; q4 < 4; ++q4) { as4[q4] = *(LAS f32x4*)(arr + 256 + 32 * sti + 8 * q4 + 4 * hh);
; #pragma unroll
;                         for (int e = 0; e < 4; ++e) Gt[4 * q4 + e] = Gt[4 * q4 + e] * as4[q4][e] * fl; }
.LBB0_1309:
	s_andn2_b64 vcc, exec, s[66:67]
	s_cbranch_vccnz .LBB0_1306
	s_add_i32 s66, s68, 0
	v_mov_b32_e32 v186, s66
	ds_read_b32 v235, v186
	v_add_u32_e32 v186, 0x1e800, v233
	v_add_u32_e32 v191, 0x1e820, v233
	v_add_u32_e32 v194, 0x1e840, v233
	v_add_u32_e32 v198, 0x1e860, v233
	ds_read_b128 v[186:189], v186
	ds_read_b128 v[190:193], v191
	ds_read_b128 v[194:197], v194
	ds_read_b128 v[198:201], v198
	s_waitcnt lgkmcnt(4)
	v_sub_f32_e32 v235, v140, v235
	v_exp_f32_e32 v234, v235
	s_waitcnt lgkmcnt(3)
	v_pk_mul_f32 v[36:37], v[36:37], v[188:189]
	s_waitcnt lgkmcnt(2)
	v_pk_mul_f32 v[38:39], v[38:39], v[190:191]
	v_pk_mul_f32 v[40:41], v[40:41], v[192:193]
	s_waitcnt lgkmcnt(1)
	v_pk_mul_f32 v[42:43], v[42:43], v[194:195]
	v_pk_mul_f32 v[44:45], v[44:45], v[196:197]
	s_waitcnt lgkmcnt(0)
	v_pk_mul_f32 v[46:47], v[46:47], v[198:199]
	v_pk_mul_f32 v[48:49], v[48:49], v[200:201]
	v_pk_mul_f32 v[34:35], v[34:35], v[186:187]
	v_pk_mul_f32 v[200:201], v[234:235], v[48:49] op_sel_hi:[0,1]
	v_pk_mul_f32 v[198:199], v[234:235], v[46:47] op_sel_hi:[0,1]
	v_pk_mul_f32 v[196:197], v[234:235], v[44:45] op_sel_hi:[0,1]
	v_pk_mul_f32 v[194:195], v[234:235], v[42:43] op_sel_hi:[0,1]
	v_pk_mul_f32 v[192:193], v[234:235], v[40:41] op_sel_hi:[0,1]
	v_pk_mul_f32 v[190:191], v[234:235], v[38:39] op_sel_hi:[0,1]
	v_pk_mul_f32 v[188:189], v[234:235], v[36:37] op_sel_hi:[0,1]
	v_pk_mul_f32 v[186:187], v[234:235], v[34:35] op_sel_hi:[0,1]
	s_branch .LBB0_1306
